# v013 with the P8 widened stores issued after every second row instead of all at the end of the epilogue
# speedup vs baseline: 1.0060x; 1.0060x over previous
.LBB0_893:
	v_lshl_add_u32 v146, s26, 8, v154
	v_ashrrev_i32_e32 v147, 31, v146
	v_lshl_add_u64 v[144:145], v[146:147], 2, s[12:13]
	global_load_dword v170, v[144:145], off
	global_load_dword v171, v[144:145], off offset:64
	global_load_dword v172, v[144:145], off offset:128
	global_load_dword v173, v[144:145], off offset:192
	global_load_dword v174, v[144:145], off offset:512
	global_load_dword v175, v[144:145], off offset:576
	global_load_dword v176, v[144:145], off offset:640
	global_load_dword v177, v[144:145], off offset:704
	v_mul_f32_e32 v125, v124, v125
	v_mul_f32_e32 v127, v126, v127
	v_mul_f32_e32 v121, v120, v121
	v_mul_f32_e32 v123, v122, v123
	v_mul_f32_e32 v117, v116, v117
	v_mul_f32_e32 v119, v118, v119
	v_mul_f32_e32 v113, v112, v113
	v_mul_f32_e32 v115, v114, v115
	v_mul_f32_e32 v109, v108, v109
	v_mul_f32_e32 v111, v110, v111
	v_mul_f32_e32 v105, v104, v105
	v_mul_f32_e32 v107, v106, v107
	v_mul_f32_e32 v101, v100, v101
	v_mul_f32_e32 v103, v102, v103
	v_mul_f32_e32 v97, v96, v97
	v_mul_f32_e32 v99, v98, v99
	v_mul_f32_e32 v93, v92, v93
	v_mul_f32_e32 v95, v94, v95
	v_mul_f32_e32 v89, v88, v89
	v_mul_f32_e32 v91, v90, v91
	v_mul_f32_e32 v85, v84, v85
	v_mul_f32_e32 v87, v86, v87
	v_mul_f32_e32 v81, v80, v81
	v_mul_f32_e32 v83, v82, v83
	v_mul_f32_e32 v77, v76, v77
	v_mul_f32_e32 v79, v78, v79
	v_mul_f32_e32 v73, v72, v73
	v_mul_f32_e32 v75, v74, v75
	v_mul_f32_e32 v69, v68, v69
	v_mul_f32_e32 v71, v70, v71
	v_mul_f32_e32 v65, v64, v65
	v_mul_f32_e32 v67, v66, v67
	v_mul_f32_e32 v61, v60, v61
	v_mul_f32_e32 v63, v62, v63
	v_mul_f32_e32 v57, v56, v57
	v_mul_f32_e32 v59, v58, v59
	v_mul_f32_e32 v53, v52, v53
	v_mul_f32_e32 v55, v54, v55
	v_mul_f32_e32 v49, v48, v49
	v_mul_f32_e32 v51, v50, v51
	v_mul_f32_e32 v45, v44, v45
	v_mul_f32_e32 v47, v46, v47
	v_mul_f32_e32 v41, v40, v41
	v_mul_f32_e32 v43, v42, v43
	v_mul_f32_e32 v37, v36, v37
	v_mul_f32_e32 v39, v38, v39
	v_mul_f32_e32 v33, v32, v33
	v_mul_f32_e32 v35, v34, v35
	v_mul_f32_e32 v29, v28, v29
	v_mul_f32_e32 v31, v30, v31
	v_mul_f32_e32 v25, v24, v25
	v_mul_f32_e32 v27, v26, v27
	v_mul_f32_e32 v21, v20, v21
	v_mul_f32_e32 v23, v22, v23
	v_mul_f32_e32 v17, v16, v17
	v_mul_f32_e32 v19, v18, v19
	v_mul_f32_e32 v13, v12, v13
	v_mul_f32_e32 v15, v14, v15
	v_mul_f32_e32 v9, v8, v9
	v_mul_f32_e32 v11, v10, v11
	v_mul_f32_e32 v5, v4, v5
	v_mul_f32_e32 v7, v6, v7
	v_mul_f32_e32 v1, v0, v1
	v_mul_f32_e32 v3, v2, v3
	s_waitcnt vmcnt(0)
	v_lshl_or_b32 v147, s55, 8, v156
	v_mov_b64_e32 v[144:145], s[10:11]
	v_mad_i64_i32 v[166:167], s[28:29], v146, s54, v[144:145]
	v_ashrrev_i32_e32 v146, 1, v147
	v_ashrrev_i32_e32 v147, 31, v146
	v_lshlrev_b64 v[146:147], 1, v[146:147]
	v_lshl_add_u64 v[166:167], v[166:167], 0, v[146:147]
	v_lshrrev_b32_e32 v165, 4, v214
	v_and_b32_e32 v165, 1, v165
	v_mul_u32_u24_e32 v168, 0x15ff8, v165
	v_mov_b32_e32 v169, 0
	v_lshl_add_u64 v[168:169], v[166:167], 0, v[168:169]
	s_mov_b64 s[64:65], 0x2c000
	s_mov_b64 s[66:67], 0x84000
	s_andn2_b64 vcc, exec, s[2:3]
	s_mov_b64 s[2:3], -1
	v_fmamk_f32 v164, v170, 0x3a800000, v160
	v_rsq_f32_e32 v162, v164
	s_nop 0
	v_mul_f32_e32 v163, 0xbfb8aa3b, v162
	v_mul_f32_e32 v144, v163, v124
	v_mul_f32_e32 v145, v163, v126
	v_mul_f32_e32 v146, v163, v120
	v_mul_f32_e32 v147, v163, v122
	v_exp_f32_e32 v144, v144
	v_exp_f32_e32 v145, v145
	v_exp_f32_e32 v146, v146
	v_exp_f32_e32 v147, v147
	v_fma_f32 v144, v144, v164, v164
	v_fma_f32 v145, v145, v164, v164
	v_fma_f32 v146, v146, v164, v164
	v_fma_f32 v147, v147, v164, v164
	v_rcp_f32_e32 v144, v144
	v_rcp_f32_e32 v145, v145
	v_rcp_f32_e32 v146, v146
	v_rcp_f32_e32 v147, v147
	v_mul_f32_e32 v148, v125, v144
	v_mul_f32_e32 v149, v127, v145
	v_mul_f32_e32 v150, v121, v146
	v_mul_f32_e32 v151, v123, v147
	v_cvt_pk_bf16_f32 v186, v148, v149
	v_cvt_pk_bf16_f32 v187, v150, v151
	v_mul_f32_e32 v178, v163, v116
	v_mul_f32_e32 v179, v163, v118
	v_mul_f32_e32 v180, v163, v112
	v_mul_f32_e32 v181, v163, v114
	v_exp_f32_e32 v178, v178
	v_exp_f32_e32 v179, v179
	v_exp_f32_e32 v180, v180
	v_exp_f32_e32 v181, v181
	v_fma_f32 v178, v178, v164, v164
	v_fma_f32 v179, v179, v164, v164
	v_fma_f32 v180, v180, v164, v164
	v_fma_f32 v181, v181, v164, v164
	v_rcp_f32_e32 v178, v178
	v_rcp_f32_e32 v179, v179
	v_rcp_f32_e32 v180, v180
	v_rcp_f32_e32 v181, v181
	v_mul_f32_e32 v182, v117, v178
	v_mul_f32_e32 v183, v119, v179
	v_mul_f32_e32 v184, v113, v180
	v_mul_f32_e32 v185, v115, v181
	v_cvt_pk_bf16_f32 v190, v182, v183
	v_cvt_pk_bf16_f32 v191, v184, v185
	v_fmamk_f32 v164, v171, 0x3a800000, v160
	v_rsq_f32_e32 v162, v164
	s_nop 0
	v_mul_f32_e32 v163, 0xbfb8aa3b, v162
	v_mul_f32_e32 v144, v163, v108
	v_mul_f32_e32 v145, v163, v110
	v_mul_f32_e32 v146, v163, v104
	v_mul_f32_e32 v147, v163, v106
	v_exp_f32_e32 v144, v144
	v_exp_f32_e32 v145, v145
	v_exp_f32_e32 v146, v146
	v_exp_f32_e32 v147, v147
	v_fma_f32 v144, v144, v164, v164
	v_fma_f32 v145, v145, v164, v164
	v_fma_f32 v146, v146, v164, v164
	v_fma_f32 v147, v147, v164, v164
	v_rcp_f32_e32 v144, v144
	v_rcp_f32_e32 v145, v145
	v_rcp_f32_e32 v146, v146
	v_rcp_f32_e32 v147, v147
	v_mul_f32_e32 v148, v109, v144
	v_mul_f32_e32 v149, v111, v145
	v_mul_f32_e32 v150, v105, v146
	v_mul_f32_e32 v151, v107, v147
	v_cvt_pk_bf16_f32 v188, v148, v149
	v_cvt_pk_bf16_f32 v189, v150, v151
	v_mul_f32_e32 v178, v163, v100
	v_mul_f32_e32 v179, v163, v102
	v_mul_f32_e32 v180, v163, v96
	v_mul_f32_e32 v181, v163, v98
	v_exp_f32_e32 v178, v178
	v_exp_f32_e32 v179, v179
	v_exp_f32_e32 v180, v180
	v_exp_f32_e32 v181, v181
	v_fma_f32 v178, v178, v164, v164
	v_fma_f32 v179, v179, v164, v164
	v_fma_f32 v180, v180, v164, v164
	v_fma_f32 v181, v181, v164, v164
	v_rcp_f32_e32 v178, v178
	v_rcp_f32_e32 v179, v179
	v_rcp_f32_e32 v180, v180
	v_rcp_f32_e32 v181, v181
	v_mul_f32_e32 v182, v101, v178
	v_mul_f32_e32 v183, v103, v179
	v_mul_f32_e32 v184, v97, v180
	v_mul_f32_e32 v185, v99, v181
	v_cvt_pk_bf16_f32 v192, v182, v183
	v_cvt_pk_bf16_f32 v193, v184, v185
	v_permlane16_swap_b32_e32 v186, v188
	v_permlane16_swap_b32_e32 v187, v189
	global_store_dwordx4 v[168:169], v[186:189], off
	v_permlane16_swap_b32_e32 v190, v192
	v_permlane16_swap_b32_e32 v191, v193
	global_store_dwordx4 v[168:169], v[190:193], off offset:128
	v_fmamk_f32 v164, v172, 0x3a800000, v160
	v_rsq_f32_e32 v162, v164
	s_nop 0
	v_mul_f32_e32 v163, 0xbfb8aa3b, v162
	v_mul_f32_e32 v144, v163, v92
	v_mul_f32_e32 v145, v163, v94
	v_mul_f32_e32 v146, v163, v88
	v_mul_f32_e32 v147, v163, v90
	v_exp_f32_e32 v144, v144
	v_exp_f32_e32 v145, v145
	v_exp_f32_e32 v146, v146
	v_exp_f32_e32 v147, v147
	v_fma_f32 v144, v144, v164, v164
	v_fma_f32 v145, v145, v164, v164
	v_fma_f32 v146, v146, v164, v164
	v_fma_f32 v147, v147, v164, v164
	v_rcp_f32_e32 v144, v144
	v_rcp_f32_e32 v145, v145
	v_rcp_f32_e32 v146, v146
	v_rcp_f32_e32 v147, v147
	v_mul_f32_e32 v148, v93, v144
	v_mul_f32_e32 v149, v95, v145
	v_mul_f32_e32 v150, v89, v146
	v_mul_f32_e32 v151, v91, v147
	v_cvt_pk_bf16_f32 v194, v148, v149
	v_cvt_pk_bf16_f32 v195, v150, v151
	v_mul_f32_e32 v178, v163, v84
	v_mul_f32_e32 v179, v163, v86
	v_mul_f32_e32 v180, v163, v80
	v_mul_f32_e32 v181, v163, v82
	v_exp_f32_e32 v178, v178
	v_exp_f32_e32 v179, v179
	v_exp_f32_e32 v180, v180
	v_exp_f32_e32 v181, v181
	v_fma_f32 v178, v178, v164, v164
	v_fma_f32 v179, v179, v164, v164
	v_fma_f32 v180, v180, v164, v164
	v_fma_f32 v181, v181, v164, v164
	v_rcp_f32_e32 v178, v178
	v_rcp_f32_e32 v179, v179
	v_rcp_f32_e32 v180, v180
	v_rcp_f32_e32 v181, v181
	v_mul_f32_e32 v182, v85, v178
	v_mul_f32_e32 v183, v87, v179
	v_mul_f32_e32 v184, v81, v180
	v_mul_f32_e32 v185, v83, v181
	v_cvt_pk_bf16_f32 v198, v182, v183
	v_cvt_pk_bf16_f32 v199, v184, v185
	v_fmamk_f32 v164, v173, 0x3a800000, v160
	v_rsq_f32_e32 v162, v164
	s_nop 0
	v_mul_f32_e32 v163, 0xbfb8aa3b, v162
	v_mul_f32_e32 v144, v163, v76
	v_mul_f32_e32 v145, v163, v78
	v_mul_f32_e32 v146, v163, v72
	v_mul_f32_e32 v147, v163, v74
	v_exp_f32_e32 v144, v144
	v_exp_f32_e32 v145, v145
	v_exp_f32_e32 v146, v146
	v_exp_f32_e32 v147, v147
	v_fma_f32 v144, v144, v164, v164
	v_fma_f32 v145, v145, v164, v164
	v_fma_f32 v146, v146, v164, v164
	v_fma_f32 v147, v147, v164, v164
	v_rcp_f32_e32 v144, v144
	v_rcp_f32_e32 v145, v145
	v_rcp_f32_e32 v146, v146
	v_rcp_f32_e32 v147, v147
	v_mul_f32_e32 v148, v77, v144
	v_mul_f32_e32 v149, v79, v145
	v_mul_f32_e32 v150, v73, v146
	v_mul_f32_e32 v151, v75, v147
	v_cvt_pk_bf16_f32 v196, v148, v149
	v_cvt_pk_bf16_f32 v197, v150, v151
	v_mul_f32_e32 v178, v163, v68
	v_mul_f32_e32 v179, v163, v70
	v_mul_f32_e32 v180, v163, v64
	v_mul_f32_e32 v181, v163, v66
	v_exp_f32_e32 v178, v178
	v_exp_f32_e32 v179, v179
	v_exp_f32_e32 v180, v180
	v_exp_f32_e32 v181, v181
	v_fma_f32 v178, v178, v164, v164
	v_fma_f32 v179, v179, v164, v164
	v_fma_f32 v180, v180, v164, v164
	v_fma_f32 v181, v181, v164, v164
	v_rcp_f32_e32 v178, v178
	v_rcp_f32_e32 v179, v179
	v_rcp_f32_e32 v180, v180
	v_rcp_f32_e32 v181, v181
	v_mul_f32_e32 v182, v69, v178
	v_mul_f32_e32 v183, v71, v179
	v_mul_f32_e32 v184, v65, v180
	v_mul_f32_e32 v185, v67, v181
	v_cvt_pk_bf16_f32 v200, v182, v183
	v_cvt_pk_bf16_f32 v201, v184, v185
	v_lshl_add_u64 v[168:169], v[168:169], 0, s[64:65]
	v_permlane16_swap_b32_e32 v194, v196
	v_permlane16_swap_b32_e32 v195, v197
	global_store_dwordx4 v[168:169], v[194:197], off
	v_permlane16_swap_b32_e32 v198, v200
	v_permlane16_swap_b32_e32 v199, v201
	global_store_dwordx4 v[168:169], v[198:201], off offset:128
	v_fmamk_f32 v164, v174, 0x3a800000, v160
	v_rsq_f32_e32 v162, v164
	s_nop 0
	v_mul_f32_e32 v163, 0xbfb8aa3b, v162
	v_mul_f32_e32 v144, v163, v60
	v_mul_f32_e32 v145, v163, v62
	v_mul_f32_e32 v146, v163, v56
	v_mul_f32_e32 v147, v163, v58
	v_exp_f32_e32 v144, v144
	v_exp_f32_e32 v145, v145
	v_exp_f32_e32 v146, v146
	v_exp_f32_e32 v147, v147
	v_fma_f32 v144, v144, v164, v164
	v_fma_f32 v145, v145, v164, v164
	v_fma_f32 v146, v146, v164, v164
	v_fma_f32 v147, v147, v164, v164
	v_rcp_f32_e32 v144, v144
	v_rcp_f32_e32 v145, v145
	v_rcp_f32_e32 v146, v146
	v_rcp_f32_e32 v147, v147
	v_mul_f32_e32 v148, v61, v144
	v_mul_f32_e32 v149, v63, v145
	v_mul_f32_e32 v150, v57, v146
	v_mul_f32_e32 v151, v59, v147
	v_cvt_pk_bf16_f32 v202, v148, v149
	v_cvt_pk_bf16_f32 v203, v150, v151
	v_mul_f32_e32 v178, v163, v52
	v_mul_f32_e32 v179, v163, v54
	v_mul_f32_e32 v180, v163, v48
	v_mul_f32_e32 v181, v163, v50
	v_exp_f32_e32 v178, v178
	v_exp_f32_e32 v179, v179
	v_exp_f32_e32 v180, v180
	v_exp_f32_e32 v181, v181
	v_fma_f32 v178, v178, v164, v164
	v_fma_f32 v179, v179, v164, v164
	v_fma_f32 v180, v180, v164, v164
	v_fma_f32 v181, v181, v164, v164
	v_rcp_f32_e32 v178, v178
	v_rcp_f32_e32 v179, v179
	v_rcp_f32_e32 v180, v180
	v_rcp_f32_e32 v181, v181
	v_mul_f32_e32 v182, v53, v178
	v_mul_f32_e32 v183, v55, v179
	v_mul_f32_e32 v184, v49, v180
	v_mul_f32_e32 v185, v51, v181
	v_cvt_pk_bf16_f32 v206, v182, v183
	v_cvt_pk_bf16_f32 v207, v184, v185
	v_fmamk_f32 v164, v175, 0x3a800000, v160
	v_rsq_f32_e32 v162, v164
	s_nop 0
	v_mul_f32_e32 v163, 0xbfb8aa3b, v162
	v_mul_f32_e32 v144, v163, v44
	v_mul_f32_e32 v145, v163, v46
	v_mul_f32_e32 v146, v163, v40
	v_mul_f32_e32 v147, v163, v42
	v_exp_f32_e32 v144, v144
	v_exp_f32_e32 v145, v145
	v_exp_f32_e32 v146, v146
	v_exp_f32_e32 v147, v147
	v_fma_f32 v144, v144, v164, v164
	v_fma_f32 v145, v145, v164, v164
	v_fma_f32 v146, v146, v164, v164
	v_fma_f32 v147, v147, v164, v164
	v_rcp_f32_e32 v144, v144
	v_rcp_f32_e32 v145, v145
	v_rcp_f32_e32 v146, v146
	v_rcp_f32_e32 v147, v147
	v_mul_f32_e32 v148, v45, v144
	v_mul_f32_e32 v149, v47, v145
	v_mul_f32_e32 v150, v41, v146
	v_mul_f32_e32 v151, v43, v147
	v_cvt_pk_bf16_f32 v204, v148, v149
	v_cvt_pk_bf16_f32 v205, v150, v151
	v_mul_f32_e32 v178, v163, v36
	v_mul_f32_e32 v179, v163, v38
	v_mul_f32_e32 v180, v163, v32
	v_mul_f32_e32 v181, v163, v34
	v_exp_f32_e32 v178, v178
	v_exp_f32_e32 v179, v179
	v_exp_f32_e32 v180, v180
	v_exp_f32_e32 v181, v181
	v_fma_f32 v178, v178, v164, v164
	v_fma_f32 v179, v179, v164, v164
	v_fma_f32 v180, v180, v164, v164
	v_fma_f32 v181, v181, v164, v164
	v_rcp_f32_e32 v178, v178
	v_rcp_f32_e32 v179, v179
	v_rcp_f32_e32 v180, v180
	v_rcp_f32_e32 v181, v181
	v_mul_f32_e32 v182, v37, v178
	v_mul_f32_e32 v183, v39, v179
	v_mul_f32_e32 v184, v33, v180
	v_mul_f32_e32 v185, v35, v181
	v_cvt_pk_bf16_f32 v208, v182, v183
	v_cvt_pk_bf16_f32 v209, v184, v185
	v_lshl_add_u64 v[168:169], v[168:169], 0, s[66:67]
	v_permlane16_swap_b32_e32 v202, v204
	v_permlane16_swap_b32_e32 v203, v205
	global_store_dwordx4 v[168:169], v[202:205], off
	v_permlane16_swap_b32_e32 v206, v208
	v_permlane16_swap_b32_e32 v207, v209
	global_store_dwordx4 v[168:169], v[206:209], off offset:128
	v_fmamk_f32 v164, v176, 0x3a800000, v160
	v_rsq_f32_e32 v162, v164
	s_nop 0
	v_mul_f32_e32 v163, 0xbfb8aa3b, v162
	v_mul_f32_e32 v144, v163, v28
	v_mul_f32_e32 v145, v163, v30
	v_mul_f32_e32 v146, v163, v24
	v_mul_f32_e32 v147, v163, v26
	v_exp_f32_e32 v144, v144
	v_exp_f32_e32 v145, v145
	v_exp_f32_e32 v146, v146
	v_exp_f32_e32 v147, v147
	v_fma_f32 v144, v144, v164, v164
	v_fma_f32 v145, v145, v164, v164
	v_fma_f32 v146, v146, v164, v164
	v_fma_f32 v147, v147, v164, v164
	v_rcp_f32_e32 v144, v144
	v_rcp_f32_e32 v145, v145
	v_rcp_f32_e32 v146, v146
	v_rcp_f32_e32 v147, v147
	v_mul_f32_e32 v148, v29, v144
	v_mul_f32_e32 v149, v31, v145
	v_mul_f32_e32 v150, v25, v146
	v_mul_f32_e32 v151, v27, v147
	v_cvt_pk_bf16_f32 v210, v148, v149
	v_cvt_pk_bf16_f32 v211, v150, v151
	v_mul_f32_e32 v178, v163, v20
	v_mul_f32_e32 v179, v163, v22
	v_mul_f32_e32 v180, v163, v16
	v_mul_f32_e32 v181, v163, v18
	v_exp_f32_e32 v178, v178
	v_exp_f32_e32 v179, v179
	v_exp_f32_e32 v180, v180
	v_exp_f32_e32 v181, v181
	v_fma_f32 v178, v178, v164, v164
	v_fma_f32 v179, v179, v164, v164
	v_fma_f32 v180, v180, v164, v164
	v_fma_f32 v181, v181, v164, v164
	v_rcp_f32_e32 v178, v178
	v_rcp_f32_e32 v179, v179
	v_rcp_f32_e32 v180, v180
	v_rcp_f32_e32 v181, v181
	v_mul_f32_e32 v182, v21, v178
	v_mul_f32_e32 v183, v23, v179
	v_mul_f32_e32 v184, v17, v180
	v_mul_f32_e32 v185, v19, v181
	v_cvt_pk_bf16_f32 v216, v182, v183
	v_cvt_pk_bf16_f32 v217, v184, v185
	v_fmamk_f32 v164, v177, 0x3a800000, v160
	v_rsq_f32_e32 v162, v164
	s_nop 0
	v_mul_f32_e32 v163, 0xbfb8aa3b, v162
	v_mul_f32_e32 v144, v163, v12
	v_mul_f32_e32 v145, v163, v14
	v_mul_f32_e32 v146, v163, v8
	v_mul_f32_e32 v147, v163, v10
	v_exp_f32_e32 v144, v144
	v_exp_f32_e32 v145, v145
	v_exp_f32_e32 v146, v146
	v_exp_f32_e32 v147, v147
	v_fma_f32 v144, v144, v164, v164
	v_fma_f32 v145, v145, v164, v164
	v_fma_f32 v146, v146, v164, v164
	v_fma_f32 v147, v147, v164, v164
	v_rcp_f32_e32 v144, v144
	v_rcp_f32_e32 v145, v145
	v_rcp_f32_e32 v146, v146
	v_rcp_f32_e32 v147, v147
	v_mul_f32_e32 v148, v13, v144
	v_mul_f32_e32 v149, v15, v145
	v_mul_f32_e32 v150, v9, v146
	v_mul_f32_e32 v151, v11, v147
	v_cvt_pk_bf16_f32 v212, v148, v149
	v_cvt_pk_bf16_f32 v213, v150, v151
	v_mul_f32_e32 v178, v163, v4
	v_mul_f32_e32 v179, v163, v6
	v_mul_f32_e32 v180, v163, v0
	v_mul_f32_e32 v181, v163, v2
	v_exp_f32_e32 v178, v178
	v_exp_f32_e32 v179, v179
	v_exp_f32_e32 v180, v180
	v_exp_f32_e32 v181, v181
	v_fma_f32 v178, v178, v164, v164
	v_fma_f32 v179, v179, v164, v164
	v_fma_f32 v180, v180, v164, v164
	v_fma_f32 v181, v181, v164, v164
	v_rcp_f32_e32 v178, v178
	v_rcp_f32_e32 v179, v179
	v_rcp_f32_e32 v180, v180
	v_rcp_f32_e32 v181, v181
	v_mul_f32_e32 v182, v5, v178
	v_mul_f32_e32 v183, v7, v179
	v_mul_f32_e32 v184, v1, v180
	v_mul_f32_e32 v185, v3, v181
	v_cvt_pk_bf16_f32 v218, v182, v183
	v_cvt_pk_bf16_f32 v219, v184, v185
	v_lshl_add_u64 v[168:169], v[168:169], 0, s[64:65]
	v_permlane16_swap_b32_e32 v210, v212
	v_permlane16_swap_b32_e32 v211, v213
	global_store_dwordx4 v[168:169], v[210:213], off
	v_permlane16_swap_b32_e32 v216, v218
	v_permlane16_swap_b32_e32 v217, v219
	global_store_dwordx4 v[168:169], v[216:219], off offset:128
	s_cbranch_vccnz .LBB0_886
	s_andn2_b64 vcc, exec, s[4:5]
	s_cbranch_vccnz .LBB0_885
	s_barrier
	s_branch .LBB0_885
